# GEMM K-loops: even half-step W register loads issued before the per-step barrier (DMA stays after it)
# speedup vs baseline: 1.0067x; 1.0067x over previous
.Lg1_loop:
	s_waitcnt vmcnt(12)
	global_load_dwordx4 v[176:179], v238, s[56:57]
	global_load_dwordx4 v[182:185], v239, s[56:57]
	global_load_dwordx4 v[186:189], v240, s[56:57]
	global_load_dwordx4 v[194:197], v241, s[56:57]
	s_cmp_eq_u32 s25, 31
	s_cbranch_scc1 .Lg1_sww0
	s_add_u32 s56, s56, 1024
	s_addc_u32 s57, s57, 0
	s_branch .Lg1_swdw0

.Lg1_ndw0:
.Lg1_swdw0:
	s_add_i32 s25, s25, 1
	s_barrier
	v_add_u32_e32 v244, s28, v242
	v_add_u32_e32 v245, s28, v243
	ds_read_b128 v[198:201], v244 offset:0
	ds_read_b128 v[202:205], v244 offset:2048
	ds_read_b128 v[210:213], v244 offset:4096
	ds_read_b128 v[214:217], v244 offset:6144
	ds_read_b128 v[218:221], v244 offset:8192
	ds_read_b128 v[222:225], v244 offset:10240
	ds_read_b128 v[226:229], v244 offset:12288
	ds_read_b128 v[230:233], v244 offset:14336
	s_waitcnt lgkmcnt(4)
	s_add_i32 m0, s27, s97
	v_mfma_f32_16x16x32_bf16 v[0:3], v[128:131], v[198:201], v[0:3]
	v_mfma_f32_16x16x32_bf16 v[32:35], v[132:135], v[198:201], v[32:35]
	v_mfma_f32_16x16x32_bf16 v[64:67], v[136:139], v[198:201], v[64:67]
	v_mfma_f32_16x16x32_bf16 v[96:99], v[140:143], v[198:201], v[96:99]
	global_load_lds_dwordx4 v234, s[58:59]
	s_add_i32 m0, m0, 0x400
	v_mfma_f32_16x16x32_bf16 v[4:7], v[128:131], v[202:205], v[4:7]
	v_mfma_f32_16x16x32_bf16 v[36:39], v[132:135], v[202:205], v[36:39]
	v_mfma_f32_16x16x32_bf16 v[68:71], v[136:139], v[202:205], v[68:71]
	v_mfma_f32_16x16x32_bf16 v[100:103], v[140:143], v[202:205], v[100:103]
	global_load_lds_dwordx4 v235, s[58:59]
	s_add_i32 m0, m0, 0x400
	v_mfma_f32_16x16x32_bf16 v[8:11], v[128:131], v[210:213], v[8:11]
	v_mfma_f32_16x16x32_bf16 v[40:43], v[132:135], v[210:213], v[40:43]
	v_mfma_f32_16x16x32_bf16 v[72:75], v[136:139], v[210:213], v[72:75]
	v_mfma_f32_16x16x32_bf16 v[104:107], v[140:143], v[210:213], v[104:107]
	global_load_lds_dwordx4 v236, s[58:59]
	s_add_i32 m0, m0, 0x400
	v_mfma_f32_16x16x32_bf16 v[12:15], v[128:131], v[214:217], v[12:15]
	v_mfma_f32_16x16x32_bf16 v[44:47], v[132:135], v[214:217], v[44:47]
	v_mfma_f32_16x16x32_bf16 v[76:79], v[136:139], v[214:217], v[76:79]
	v_mfma_f32_16x16x32_bf16 v[108:111], v[140:143], v[214:217], v[108:111]
	global_load_lds_dwordx4 v237, s[58:59]
	s_cmp_eq_u32 s29, 13
	s_cbranch_scc1 .Lg1_saa1
	s_add_u32 s58, s58, 128
	s_addc_u32 s59, s59, 0
	s_branch .Lg1_sada1

.Lg1_ndw2:
.Lg1_swdw2:
	s_add_i32 s25, s25, 1
	s_waitcnt lgkmcnt(4)
	v_mfma_f32_16x16x32_bf16 v[0:3], v[144:147], v[198:201], v[0:3]
	v_mfma_f32_16x16x32_bf16 v[32:35], v[148:151], v[198:201], v[32:35]
	v_mfma_f32_16x16x32_bf16 v[64:67], v[152:155], v[198:201], v[64:67]
	v_mfma_f32_16x16x32_bf16 v[96:99], v[156:159], v[198:201], v[96:99]
	v_mfma_f32_16x16x32_bf16 v[4:7], v[144:147], v[202:205], v[4:7]
	v_mfma_f32_16x16x32_bf16 v[36:39], v[148:151], v[202:205], v[36:39]
	v_mfma_f32_16x16x32_bf16 v[68:71], v[152:155], v[202:205], v[68:71]
	v_mfma_f32_16x16x32_bf16 v[100:103], v[156:159], v[202:205], v[100:103]
	v_mfma_f32_16x16x32_bf16 v[8:11], v[144:147], v[210:213], v[8:11]
	v_mfma_f32_16x16x32_bf16 v[40:43], v[148:151], v[210:213], v[40:43]
	v_mfma_f32_16x16x32_bf16 v[72:75], v[152:155], v[210:213], v[72:75]
	v_mfma_f32_16x16x32_bf16 v[104:107], v[156:159], v[210:213], v[104:107]
	v_mfma_f32_16x16x32_bf16 v[12:15], v[144:147], v[214:217], v[12:15]
	v_mfma_f32_16x16x32_bf16 v[44:47], v[148:151], v[214:217], v[44:47]
	v_mfma_f32_16x16x32_bf16 v[76:79], v[152:155], v[214:217], v[76:79]
	v_mfma_f32_16x16x32_bf16 v[108:111], v[156:159], v[214:217], v[108:111]
	s_waitcnt lgkmcnt(0)
	v_mfma_f32_16x16x32_bf16 v[16:19], v[144:147], v[218:221], v[16:19]
	v_mfma_f32_16x16x32_bf16 v[48:51], v[148:151], v[218:221], v[48:51]
	v_mfma_f32_16x16x32_bf16 v[80:83], v[152:155], v[218:221], v[80:83]
	v_mfma_f32_16x16x32_bf16 v[112:115], v[156:159], v[218:221], v[112:115]
	v_mfma_f32_16x16x32_bf16 v[20:23], v[144:147], v[222:225], v[20:23]
	v_mfma_f32_16x16x32_bf16 v[52:55], v[148:151], v[222:225], v[52:55]
	v_mfma_f32_16x16x32_bf16 v[84:87], v[152:155], v[222:225], v[84:87]
	v_mfma_f32_16x16x32_bf16 v[116:119], v[156:159], v[222:225], v[116:119]
	v_mfma_f32_16x16x32_bf16 v[24:27], v[144:147], v[226:229], v[24:27]
	v_mfma_f32_16x16x32_bf16 v[56:59], v[148:151], v[226:229], v[56:59]
	v_mfma_f32_16x16x32_bf16 v[88:91], v[152:155], v[226:229], v[88:91]
	v_mfma_f32_16x16x32_bf16 v[120:123], v[156:159], v[226:229], v[120:123]
	v_mfma_f32_16x16x32_bf16 v[28:31], v[144:147], v[230:233], v[28:31]
	v_mfma_f32_16x16x32_bf16 v[60:63], v[148:151], v[230:233], v[60:63]
	v_mfma_f32_16x16x32_bf16 v[92:95], v[152:155], v[230:233], v[92:95]
	v_mfma_f32_16x16x32_bf16 v[124:127], v[156:159], v[230:233], v[124:127]
	s_add_i32 s28, s28, 0x4000
	s_cmp_lt_u32 s28, 0xc000
	s_cselect_b32 s28, s28, 0
	s_add_i32 s27, s27, 0x4000
	s_cmp_lt_u32 s27, 0xc000
	s_cselect_b32 s27, s27, 0
	s_add_i32 s29, s29, 1
	s_waitcnt vmcnt(12)
	global_load_dwordx4 v[144:147], v238, s[56:57]
	global_load_dwordx4 v[148:151], v239, s[56:57]
	global_load_dwordx4 v[152:155], v240, s[56:57]
	global_load_dwordx4 v[156:159], v241, s[56:57]
	s_cmp_eq_u32 s25, 31
	s_cbranch_scc1 .Lg1_sww3
	s_add_u32 s56, s56, 1024
	s_addc_u32 s57, s57, 0
	s_branch .Lg1_swdw3

.Lg1_ndw3:
.Lg1_swdw3:
	s_add_i32 s25, s25, 1
	s_barrier
	v_add_u32_e32 v244, s28, v242
	v_add_u32_e32 v245, s28, v243
	ds_read_b128 v[198:201], v244 offset:0
	ds_read_b128 v[202:205], v244 offset:2048
	ds_read_b128 v[210:213], v244 offset:4096
	ds_read_b128 v[214:217], v244 offset:6144
	ds_read_b128 v[218:221], v244 offset:8192
	ds_read_b128 v[222:225], v244 offset:10240
	ds_read_b128 v[226:229], v244 offset:12288
	ds_read_b128 v[230:233], v244 offset:14336
	s_waitcnt lgkmcnt(4)
	s_add_i32 m0, s27, s97
	v_mfma_f32_16x16x32_bf16 v[0:3], v[160:163], v[198:201], v[0:3]
	v_mfma_f32_16x16x32_bf16 v[32:35], v[164:167], v[198:201], v[32:35]
	v_mfma_f32_16x16x32_bf16 v[64:67], v[168:171], v[198:201], v[64:67]
	v_mfma_f32_16x16x32_bf16 v[96:99], v[172:175], v[198:201], v[96:99]
	global_load_lds_dwordx4 v234, s[58:59]
	s_add_i32 m0, m0, 0x400
	v_mfma_f32_16x16x32_bf16 v[4:7], v[160:163], v[202:205], v[4:7]
	v_mfma_f32_16x16x32_bf16 v[36:39], v[164:167], v[202:205], v[36:39]
	v_mfma_f32_16x16x32_bf16 v[68:71], v[168:171], v[202:205], v[68:71]
	v_mfma_f32_16x16x32_bf16 v[100:103], v[172:175], v[202:205], v[100:103]
	global_load_lds_dwordx4 v235, s[58:59]
	s_add_i32 m0, m0, 0x400
	v_mfma_f32_16x16x32_bf16 v[8:11], v[160:163], v[210:213], v[8:11]
	v_mfma_f32_16x16x32_bf16 v[40:43], v[164:167], v[210:213], v[40:43]
	v_mfma_f32_16x16x32_bf16 v[72:75], v[168:171], v[210:213], v[72:75]
	v_mfma_f32_16x16x32_bf16 v[104:107], v[172:175], v[210:213], v[104:107]
	global_load_lds_dwordx4 v236, s[58:59]
	s_add_i32 m0, m0, 0x400
	v_mfma_f32_16x16x32_bf16 v[12:15], v[160:163], v[214:217], v[12:15]
	v_mfma_f32_16x16x32_bf16 v[44:47], v[164:167], v[214:217], v[44:47]
	v_mfma_f32_16x16x32_bf16 v[76:79], v[168:171], v[214:217], v[76:79]
	v_mfma_f32_16x16x32_bf16 v[108:111], v[172:175], v[214:217], v[108:111]
	global_load_lds_dwordx4 v237, s[58:59]
	s_cmp_eq_u32 s29, 13
	s_cbranch_scc1 .Lg1_saa4
	s_add_u32 s58, s58, 128
	s_addc_u32 s59, s59, 0
	s_branch .Lg1_sada4

.Lg2_loop:
	s_waitcnt vmcnt(12)
	global_load_dwordx4 v[176:179], v238, s[54:55]
	global_load_dwordx4 v[184:187], v239, s[54:55]
	global_load_dwordx4 v[188:191], v240, s[54:55]
	global_load_dwordx4 v[196:199], v241, s[54:55]
	s_cmp_eq_u32 s59, 31
	s_cbranch_scc1 .Lg2_sww0
	s_add_u32 s54, s54, 1024
	s_addc_u32 s55, s55, 0
	s_branch .Lg2_swdw0

.Lg2_wndw0:
.Lg2_swdw0:
	s_add_i32 s59, s59, 1
	s_barrier
	v_add_u32_e32 v244, s56, v242
	v_add_u32_e32 v245, s56, v243
	ds_read_b128 v[200:203], v244 offset:0
	ds_read_b128 v[204:207], v244 offset:2048
	ds_read_b128 v[210:213], v244 offset:4096
	ds_read_b128 v[214:217], v244 offset:6144
	ds_read_b128 v[218:221], v244 offset:8192
	ds_read_b128 v[222:225], v244 offset:10240
	ds_read_b128 v[226:229], v244 offset:12288
	ds_read_b128 v[230:233], v244 offset:14336
	s_waitcnt lgkmcnt(4)
	s_add_i32 m0, s57, s60
	v_mfma_f32_16x16x32_bf16 v[0:3], v[128:131], v[200:203], v[0:3]
	v_mfma_f32_16x16x32_bf16 v[32:35], v[132:135], v[200:203], v[32:35]
	v_mfma_f32_16x16x32_bf16 v[64:67], v[136:139], v[200:203], v[64:67]
	v_mfma_f32_16x16x32_bf16 v[96:99], v[140:143], v[200:203], v[96:99]
	global_load_lds_dwordx4 v234, s[52:53]
	s_add_i32 m0, m0, 0x400
	v_mfma_f32_16x16x32_bf16 v[4:7], v[128:131], v[204:207], v[4:7]
	v_mfma_f32_16x16x32_bf16 v[36:39], v[132:135], v[204:207], v[36:39]
	v_mfma_f32_16x16x32_bf16 v[68:71], v[136:139], v[204:207], v[68:71]
	v_mfma_f32_16x16x32_bf16 v[100:103], v[140:143], v[204:207], v[100:103]
	global_load_lds_dwordx4 v235, s[52:53]
	s_add_i32 m0, m0, 0x400
	v_mfma_f32_16x16x32_bf16 v[8:11], v[128:131], v[210:213], v[8:11]
	v_mfma_f32_16x16x32_bf16 v[40:43], v[132:135], v[210:213], v[40:43]
	v_mfma_f32_16x16x32_bf16 v[72:75], v[136:139], v[210:213], v[72:75]
	v_mfma_f32_16x16x32_bf16 v[104:107], v[140:143], v[210:213], v[104:107]
	global_load_lds_dwordx4 v236, s[52:53]
	s_add_i32 m0, m0, 0x400
	v_mfma_f32_16x16x32_bf16 v[12:15], v[128:131], v[214:217], v[12:15]
	v_mfma_f32_16x16x32_bf16 v[44:47], v[132:135], v[214:217], v[44:47]
	v_mfma_f32_16x16x32_bf16 v[76:79], v[136:139], v[214:217], v[76:79]
	v_mfma_f32_16x16x32_bf16 v[108:111], v[140:143], v[214:217], v[108:111]
	global_load_lds_dwordx4 v237, s[52:53]
	s_cmp_eq_u32 s58, 13
	s_cbranch_scc1 .Lg2_saa1
	s_add_u32 s52, s52, 128
	s_addc_u32 s53, s53, 0
	s_branch .Lg2_sada1

.Lg2_wndw2:
.Lg2_swdw2:
	s_add_i32 s59, s59, 1
	s_waitcnt lgkmcnt(4)
	v_mfma_f32_16x16x32_bf16 v[0:3], v[144:147], v[200:203], v[0:3]
	v_mfma_f32_16x16x32_bf16 v[32:35], v[148:151], v[200:203], v[32:35]
	v_mfma_f32_16x16x32_bf16 v[64:67], v[152:155], v[200:203], v[64:67]
	v_mfma_f32_16x16x32_bf16 v[96:99], v[156:159], v[200:203], v[96:99]
	v_mfma_f32_16x16x32_bf16 v[4:7], v[144:147], v[204:207], v[4:7]
	v_mfma_f32_16x16x32_bf16 v[36:39], v[148:151], v[204:207], v[36:39]
	v_mfma_f32_16x16x32_bf16 v[68:71], v[152:155], v[204:207], v[68:71]
	v_mfma_f32_16x16x32_bf16 v[100:103], v[156:159], v[204:207], v[100:103]
	v_mfma_f32_16x16x32_bf16 v[8:11], v[144:147], v[210:213], v[8:11]
	v_mfma_f32_16x16x32_bf16 v[40:43], v[148:151], v[210:213], v[40:43]
	v_mfma_f32_16x16x32_bf16 v[72:75], v[152:155], v[210:213], v[72:75]
	v_mfma_f32_16x16x32_bf16 v[104:107], v[156:159], v[210:213], v[104:107]
	v_mfma_f32_16x16x32_bf16 v[12:15], v[144:147], v[214:217], v[12:15]
	v_mfma_f32_16x16x32_bf16 v[44:47], v[148:151], v[214:217], v[44:47]
	v_mfma_f32_16x16x32_bf16 v[76:79], v[152:155], v[214:217], v[76:79]
	v_mfma_f32_16x16x32_bf16 v[108:111], v[156:159], v[214:217], v[108:111]
	s_waitcnt lgkmcnt(0)
	v_mfma_f32_16x16x32_bf16 v[16:19], v[144:147], v[218:221], v[16:19]
	v_mfma_f32_16x16x32_bf16 v[48:51], v[148:151], v[218:221], v[48:51]
	v_mfma_f32_16x16x32_bf16 v[80:83], v[152:155], v[218:221], v[80:83]
	v_mfma_f32_16x16x32_bf16 v[112:115], v[156:159], v[218:221], v[112:115]
	v_mfma_f32_16x16x32_bf16 v[20:23], v[144:147], v[222:225], v[20:23]
	v_mfma_f32_16x16x32_bf16 v[52:55], v[148:151], v[222:225], v[52:55]
	v_mfma_f32_16x16x32_bf16 v[84:87], v[152:155], v[222:225], v[84:87]
	v_mfma_f32_16x16x32_bf16 v[116:119], v[156:159], v[222:225], v[116:119]
	v_mfma_f32_16x16x32_bf16 v[24:27], v[144:147], v[226:229], v[24:27]
	v_mfma_f32_16x16x32_bf16 v[56:59], v[148:151], v[226:229], v[56:59]
	v_mfma_f32_16x16x32_bf16 v[88:91], v[152:155], v[226:229], v[88:91]
	v_mfma_f32_16x16x32_bf16 v[120:123], v[156:159], v[226:229], v[120:123]
	v_mfma_f32_16x16x32_bf16 v[28:31], v[144:147], v[230:233], v[28:31]
	v_mfma_f32_16x16x32_bf16 v[60:63], v[148:151], v[230:233], v[60:63]
	v_mfma_f32_16x16x32_bf16 v[92:95], v[152:155], v[230:233], v[92:95]
	v_mfma_f32_16x16x32_bf16 v[124:127], v[156:159], v[230:233], v[124:127]
	s_add_i32 s56, s56, 0x4000
	s_cmp_lt_u32 s56, 0xc000
	s_cselect_b32 s56, s56, 0
	s_add_i32 s57, s57, 0x4000
	s_cmp_lt_u32 s57, 0xc000
	s_cselect_b32 s57, s57, 0
	s_add_i32 s58, s58, 1
	s_waitcnt vmcnt(12)
	global_load_dwordx4 v[144:147], v238, s[54:55]
	global_load_dwordx4 v[148:151], v239, s[54:55]
	global_load_dwordx4 v[152:155], v240, s[54:55]
	global_load_dwordx4 v[156:159], v241, s[54:55]
	s_cmp_eq_u32 s59, 31
	s_cbranch_scc1 .Lg2_sww3
	s_add_u32 s54, s54, 1024
	s_addc_u32 s55, s55, 0
	s_branch .Lg2_swdw3

.Lg2_wndw3:
.Lg2_swdw3:
	s_add_i32 s59, s59, 1
	s_barrier
	v_add_u32_e32 v244, s56, v242
	v_add_u32_e32 v245, s56, v243
	ds_read_b128 v[200:203], v244 offset:0
	ds_read_b128 v[204:207], v244 offset:2048
	ds_read_b128 v[210:213], v244 offset:4096
	ds_read_b128 v[214:217], v244 offset:6144
	ds_read_b128 v[218:221], v244 offset:8192
	ds_read_b128 v[222:225], v244 offset:10240
	ds_read_b128 v[226:229], v244 offset:12288
	ds_read_b128 v[230:233], v244 offset:14336
	s_waitcnt lgkmcnt(4)
	s_add_i32 m0, s57, s60
	v_mfma_f32_16x16x32_bf16 v[0:3], v[160:163], v[200:203], v[0:3]
	v_mfma_f32_16x16x32_bf16 v[32:35], v[164:167], v[200:203], v[32:35]
	v_mfma_f32_16x16x32_bf16 v[64:67], v[168:171], v[200:203], v[64:67]
	v_mfma_f32_16x16x32_bf16 v[96:99], v[172:175], v[200:203], v[96:99]
	global_load_lds_dwordx4 v234, s[52:53]
	s_add_i32 m0, m0, 0x400
	v_mfma_f32_16x16x32_bf16 v[4:7], v[160:163], v[204:207], v[4:7]
	v_mfma_f32_16x16x32_bf16 v[36:39], v[164:167], v[204:207], v[36:39]
	v_mfma_f32_16x16x32_bf16 v[68:71], v[168:171], v[204:207], v[68:71]
	v_mfma_f32_16x16x32_bf16 v[100:103], v[172:175], v[204:207], v[100:103]
	global_load_lds_dwordx4 v235, s[52:53]
	s_add_i32 m0, m0, 0x400
	v_mfma_f32_16x16x32_bf16 v[8:11], v[160:163], v[210:213], v[8:11]
	v_mfma_f32_16x16x32_bf16 v[40:43], v[164:167], v[210:213], v[40:43]
	v_mfma_f32_16x16x32_bf16 v[72:75], v[168:171], v[210:213], v[72:75]
	v_mfma_f32_16x16x32_bf16 v[104:107], v[172:175], v[210:213], v[104:107]
	global_load_lds_dwordx4 v236, s[52:53]
	s_add_i32 m0, m0, 0x400
	v_mfma_f32_16x16x32_bf16 v[12:15], v[160:163], v[214:217], v[12:15]
	v_mfma_f32_16x16x32_bf16 v[44:47], v[164:167], v[214:217], v[44:47]
	v_mfma_f32_16x16x32_bf16 v[76:79], v[168:171], v[214:217], v[76:79]
	v_mfma_f32_16x16x32_bf16 v[108:111], v[172:175], v[214:217], v[108:111]
	global_load_lds_dwordx4 v237, s[52:53]
	s_cmp_eq_u32 s58, 13
	s_cbranch_scc1 .Lg2_saa4
	s_add_u32 s52, s52, 128
	s_addc_u32 s53, s53, 0
	s_branch .Lg2_sada4

.Lg3_loop:
	s_waitcnt vmcnt(12)
	global_load_dwordx4 v[176:179], v238, s[14:15]
	global_load_dwordx4 v[182:185], v239, s[14:15]
	global_load_dwordx4 v[186:189], v240, s[14:15]
	global_load_dwordx4 v[194:197], v241, s[14:15]
	s_cmp_eq_u32 s19, 31
	s_cbranch_scc1 .Lg3_sww0
	s_add_u32 s14, s14, 1024
	s_addc_u32 s15, s15, 0
	s_branch .Lg3_swdw0

.Lg3_wndw0:
.Lg3_swdw0:
	s_add_i32 s19, s19, 1
	s_barrier
	v_add_u32_e32 v244, s16, v242
	v_add_u32_e32 v245, s16, v243
	ds_read_b128 v[198:201], v244 offset:0
	ds_read_b128 v[202:205], v244 offset:2048
	ds_read_b128 v[210:213], v244 offset:4096
	ds_read_b128 v[214:217], v244 offset:6144
	ds_read_b128 v[218:221], v244 offset:8192
	ds_read_b128 v[222:225], v244 offset:10240
	ds_read_b128 v[226:229], v244 offset:12288
	ds_read_b128 v[230:233], v244 offset:14336
	s_waitcnt lgkmcnt(4)
	s_add_i32 m0, s17, s20
	v_mfma_f32_16x16x32_bf16 v[0:3], v[128:131], v[198:201], v[0:3]
	v_mfma_f32_16x16x32_bf16 v[32:35], v[132:135], v[198:201], v[32:35]
	v_mfma_f32_16x16x32_bf16 v[64:67], v[136:139], v[198:201], v[64:67]
	v_mfma_f32_16x16x32_bf16 v[96:99], v[140:143], v[198:201], v[96:99]
	global_load_lds_dwordx4 v234, s[12:13]
	s_add_i32 m0, m0, 0x400
	v_mfma_f32_16x16x32_bf16 v[4:7], v[128:131], v[202:205], v[4:7]
	v_mfma_f32_16x16x32_bf16 v[36:39], v[132:135], v[202:205], v[36:39]
	v_mfma_f32_16x16x32_bf16 v[68:71], v[136:139], v[202:205], v[68:71]
	v_mfma_f32_16x16x32_bf16 v[100:103], v[140:143], v[202:205], v[100:103]
	global_load_lds_dwordx4 v235, s[12:13]
	s_add_i32 m0, m0, 0x400
	v_mfma_f32_16x16x32_bf16 v[8:11], v[128:131], v[210:213], v[8:11]
	v_mfma_f32_16x16x32_bf16 v[40:43], v[132:135], v[210:213], v[40:43]
	v_mfma_f32_16x16x32_bf16 v[72:75], v[136:139], v[210:213], v[72:75]
	v_mfma_f32_16x16x32_bf16 v[104:107], v[140:143], v[210:213], v[104:107]
	global_load_lds_dwordx4 v236, s[12:13]
	s_add_i32 m0, m0, 0x400
	v_mfma_f32_16x16x32_bf16 v[12:15], v[128:131], v[214:217], v[12:15]
	v_mfma_f32_16x16x32_bf16 v[44:47], v[132:135], v[214:217], v[44:47]
	v_mfma_f32_16x16x32_bf16 v[76:79], v[136:139], v[214:217], v[76:79]
	v_mfma_f32_16x16x32_bf16 v[108:111], v[140:143], v[214:217], v[108:111]
	global_load_lds_dwordx4 v237, s[12:13]
	s_cmp_eq_u32 s18, 13
	s_cbranch_scc1 .Lg3_saa1
	s_add_u32 s12, s12, 128
	s_addc_u32 s13, s13, 0
	s_branch .Lg3_sada1

.Lg3_wndw2:
.Lg3_swdw2:
	s_add_i32 s19, s19, 1
	s_waitcnt lgkmcnt(4)
	v_mfma_f32_16x16x32_bf16 v[0:3], v[144:147], v[198:201], v[0:3]
	v_mfma_f32_16x16x32_bf16 v[32:35], v[148:151], v[198:201], v[32:35]
	v_mfma_f32_16x16x32_bf16 v[64:67], v[152:155], v[198:201], v[64:67]
	v_mfma_f32_16x16x32_bf16 v[96:99], v[156:159], v[198:201], v[96:99]
	v_mfma_f32_16x16x32_bf16 v[4:7], v[144:147], v[202:205], v[4:7]
	v_mfma_f32_16x16x32_bf16 v[36:39], v[148:151], v[202:205], v[36:39]
	v_mfma_f32_16x16x32_bf16 v[68:71], v[152:155], v[202:205], v[68:71]
	v_mfma_f32_16x16x32_bf16 v[100:103], v[156:159], v[202:205], v[100:103]
	v_mfma_f32_16x16x32_bf16 v[8:11], v[144:147], v[210:213], v[8:11]
	v_mfma_f32_16x16x32_bf16 v[40:43], v[148:151], v[210:213], v[40:43]
	v_mfma_f32_16x16x32_bf16 v[72:75], v[152:155], v[210:213], v[72:75]
	v_mfma_f32_16x16x32_bf16 v[104:107], v[156:159], v[210:213], v[104:107]
	v_mfma_f32_16x16x32_bf16 v[12:15], v[144:147], v[214:217], v[12:15]
	v_mfma_f32_16x16x32_bf16 v[44:47], v[148:151], v[214:217], v[44:47]
	v_mfma_f32_16x16x32_bf16 v[76:79], v[152:155], v[214:217], v[76:79]
	v_mfma_f32_16x16x32_bf16 v[108:111], v[156:159], v[214:217], v[108:111]
	s_waitcnt lgkmcnt(0)
	v_mfma_f32_16x16x32_bf16 v[16:19], v[144:147], v[218:221], v[16:19]
	v_mfma_f32_16x16x32_bf16 v[48:51], v[148:151], v[218:221], v[48:51]
	v_mfma_f32_16x16x32_bf16 v[80:83], v[152:155], v[218:221], v[80:83]
	v_mfma_f32_16x16x32_bf16 v[112:115], v[156:159], v[218:221], v[112:115]
	v_mfma_f32_16x16x32_bf16 v[20:23], v[144:147], v[222:225], v[20:23]
	v_mfma_f32_16x16x32_bf16 v[52:55], v[148:151], v[222:225], v[52:55]
	v_mfma_f32_16x16x32_bf16 v[84:87], v[152:155], v[222:225], v[84:87]
	v_mfma_f32_16x16x32_bf16 v[116:119], v[156:159], v[222:225], v[116:119]
	v_mfma_f32_16x16x32_bf16 v[24:27], v[144:147], v[226:229], v[24:27]
	v_mfma_f32_16x16x32_bf16 v[56:59], v[148:151], v[226:229], v[56:59]
	v_mfma_f32_16x16x32_bf16 v[88:91], v[152:155], v[226:229], v[88:91]
	v_mfma_f32_16x16x32_bf16 v[120:123], v[156:159], v[226:229], v[120:123]
	v_mfma_f32_16x16x32_bf16 v[28:31], v[144:147], v[230:233], v[28:31]
	v_mfma_f32_16x16x32_bf16 v[60:63], v[148:151], v[230:233], v[60:63]
	v_mfma_f32_16x16x32_bf16 v[92:95], v[152:155], v[230:233], v[92:95]
	v_mfma_f32_16x16x32_bf16 v[124:127], v[156:159], v[230:233], v[124:127]
	s_add_i32 s16, s16, 0x4000
	s_cmp_lt_u32 s16, 0xc000
	s_cselect_b32 s16, s16, 0
	s_add_i32 s17, s17, 0x4000
	s_cmp_lt_u32 s17, 0xc000
	s_cselect_b32 s17, s17, 0
	s_add_i32 s18, s18, 1
	s_waitcnt vmcnt(12)
	global_load_dwordx4 v[144:147], v238, s[14:15]
	global_load_dwordx4 v[148:151], v239, s[14:15]
	global_load_dwordx4 v[152:155], v240, s[14:15]
	global_load_dwordx4 v[156:159], v241, s[14:15]
	s_cmp_eq_u32 s19, 31
	s_cbranch_scc1 .Lg3_sww3
	s_add_u32 s14, s14, 1024
	s_addc_u32 s15, s15, 0
	s_branch .Lg3_swdw3

.Lg3_wndw3:
.Lg3_swdw3:
	s_add_i32 s19, s19, 1
	s_barrier
	v_add_u32_e32 v244, s16, v242
	v_add_u32_e32 v245, s16, v243
	ds_read_b128 v[198:201], v244 offset:0
	ds_read_b128 v[202:205], v244 offset:2048
	ds_read_b128 v[210:213], v244 offset:4096
	ds_read_b128 v[214:217], v244 offset:6144
	ds_read_b128 v[218:221], v244 offset:8192
	ds_read_b128 v[222:225], v244 offset:10240
	ds_read_b128 v[226:229], v244 offset:12288
	ds_read_b128 v[230:233], v244 offset:14336
	s_waitcnt lgkmcnt(4)
	s_add_i32 m0, s17, s20
	v_mfma_f32_16x16x32_bf16 v[0:3], v[160:163], v[198:201], v[0:3]
	v_mfma_f32_16x16x32_bf16 v[32:35], v[164:167], v[198:201], v[32:35]
	v_mfma_f32_16x16x32_bf16 v[64:67], v[168:171], v[198:201], v[64:67]
	v_mfma_f32_16x16x32_bf16 v[96:99], v[172:175], v[198:201], v[96:99]
	global_load_lds_dwordx4 v234, s[12:13]
	s_add_i32 m0, m0, 0x400
	v_mfma_f32_16x16x32_bf16 v[4:7], v[160:163], v[202:205], v[4:7]
	v_mfma_f32_16x16x32_bf16 v[36:39], v[164:167], v[202:205], v[36:39]
	v_mfma_f32_16x16x32_bf16 v[68:71], v[168:171], v[202:205], v[68:71]
	v_mfma_f32_16x16x32_bf16 v[100:103], v[172:175], v[202:205], v[100:103]
	global_load_lds_dwordx4 v235, s[12:13]
	s_add_i32 m0, m0, 0x400
	v_mfma_f32_16x16x32_bf16 v[8:11], v[160:163], v[210:213], v[8:11]
	v_mfma_f32_16x16x32_bf16 v[40:43], v[164:167], v[210:213], v[40:43]
	v_mfma_f32_16x16x32_bf16 v[72:75], v[168:171], v[210:213], v[72:75]
	v_mfma_f32_16x16x32_bf16 v[104:107], v[172:175], v[210:213], v[104:107]
	global_load_lds_dwordx4 v236, s[12:13]
	s_add_i32 m0, m0, 0x400
	v_mfma_f32_16x16x32_bf16 v[12:15], v[160:163], v[214:217], v[12:15]
	v_mfma_f32_16x16x32_bf16 v[44:47], v[164:167], v[214:217], v[44:47]
	v_mfma_f32_16x16x32_bf16 v[76:79], v[168:171], v[214:217], v[76:79]
	v_mfma_f32_16x16x32_bf16 v[108:111], v[172:175], v[214:217], v[108:111]
	global_load_lds_dwordx4 v237, s[12:13]
	s_cmp_eq_u32 s18, 13
	s_cbranch_scc1 .Lg3_saa4
	s_add_u32 s12, s12, 128
	s_addc_u32 s13, s13, 0
	s_branch .Lg3_sada4
